# v114 + code placement: whole attention phase shifted by 4 bytes (s_nop at its entry, compensated at its exit)
# baseline (speedup 1.0000x reference)
; __device__ __forceinline__ void xcd_barrier(const XcdBarrier& b) {
;     ...
;     __syncthreads();
; __device__ __forceinline__ void attention_phase(const Params& p, LAS unsigned char* lds, int G, int blk) {
;     float s1 = 0.f, s2 = 0.f;
;     for (int i = 0; i < 64; ++i) { s1 += p.lq1[i] * p.lk1[i]; s2 += p.lq2[i] * p.lk2[i]; }
;     const float lam = expf(s1) - expf(s2) + 0.2f;
.LBB0_260:
	s_nop 0
	s_or_b64 exec, exec, s[4:5]
	v_mov_b32_e32 v2, 0
	s_mov_b64 s[4:5], 0
	s_waitcnt lgkmcnt(0)
	v_mov_b32_e32 v0, 0
	v_mov_b32_e32 v1, v2
	s_barrier

; template <int GI>
; __device__ __forceinline__ bool sched_next(unsigned char* ws, int i, int G, int c, GUnit& u) {
;     ...
;         { constexpr int q = nwg / 8, r = nwg % 8; const int xcd = wgid % 8, off = wgid / 8; wgid = (xcd < r ? xcd * (q + 1) : r * (q + 1) + (xcd - r) * q) + off; }
;         constexpr int nig = 8 * d.nN; const int gid = wgid / nig, fm = gid * 8, gsz = (d.nM - fm) < 8 ? (d.nM - fm) : 8;
;         const int pm = fm + ((wgid % nig) % gsz), pn = (wgid % nig) / gsz;
; template <int GI>
; __device__ __forceinline__ void gemm_phase(LAS unsigned char* lds, unsigned char* ws, int G, int cblk) {
;     ...
;     if (!sched_next<GI>(ws, 0, G, cblk, cur)) return;
.LBB0_383:
	s_nop 0
	s_or_b64 exec, exec, s[4:5]
	v_mov_b32_e32 v8, v162
	s_waitcnt lgkmcnt(0)
	v_cndmask_b32_e64 v0, 0, 1, s[12:13]
	s_barrier
	v_cmp_ne_u32_e64 s[10:11], 1, v0
	s_andn2_b64 vcc, exec, s[12:13]
	v_readfirstlane_b32 s14, v8
	s_cbranch_vccnz .LBB0_407
	s_ashr_i32 s0, s2, 31
	s_lshr_b32 s0, s0, 29
	s_add_i32 s0, s2, s0
	s_and_b32 s1, s0, -8
	s_sub_i32 s3, s2, s1
	s_cmp_gt_i32 s3, -1
	s_cbranch_scc0 .LBB0_386
	s_lshl_b32 s1, s3, 7
	s_cbranch_execz .LBB0_387
	s_branch .LBB0_388
